# barrier-time weight prefetch deepened to the first 8 K-tiles (1 KB per weight row)
# baseline (speedup 1.0000x reference)
; #define GSYNC() xcd_barrier(xbar)
; __global__ void __launch_bounds__(512, 2) fwd_megakernel(Params p) {
;     ...
;     GSYNC();
;     { pg8::Gemm g{(const bf16_t*)(ws + WS_MIX), (const bf16_t*)(ws + WS_WOUT)};
;       pg8::StaticOrder S; S.init(MTOK, DM, G, bx);
;       pg8::EpiRes<false, false, true> E{p.x, nullptr, (bf16_t*)(ws + WS_HB), (float*)(ws + WS_SUMSQ1)};
;       pg8::gemm_phase<pg8::GeoPlain<DM>>(lds, g, S, E); }
.Lea_4:
	s_cmp_eq_u32 s100, 2
	s_cbranch_scc0 .Lepf_4
	v_readlane_b32 s100, v253, 2
	v_readlane_b32 s101, v253, 3
	s_sub_u32 s100, s100, 0x80200
	s_subb_u32 s101, s101, 0
	s_add_u32 s100, s100, 0x900000
	s_addc_u32 s101, s101, 0
	s_lshr_b32 s99, s2, 3
	s_lshl_b32 s99, s99, 6
	v_and_b32_e32 v224, 63, v208
	v_add_u32_e32 v224, s99, v224
	v_lshrrev_b32_e32 v225, 3, v224
	v_and_b32_e32 v224, 7, v224
	v_lshlrev_b32_e32 v224, 7, v224
	v_lshl_add_u32 v224, v225, 11, v224
	global_load_dword v226, v224, s[100:101]
	v_add_u32_e32 v224, 0x80000, v224
	global_load_dword v226, v224, s[100:101]
	v_add_u32_e32 v224, 0x80000, v224
	global_load_dword v226, v224, s[100:101]
	v_add_u32_e32 v224, 0x80000, v224
	global_load_dword v226, v224, s[100:101]

; #define GSYNC() xcd_barrier(xbar)
; __global__ void __launch_bounds__(512, 2) fwd_megakernel(Params p) {
;     ...
;     GSYNC();
;     for (int rep = 0; rep < (PROBE_ID == 6 ? 2 : 1); ++rep) {
;     { pg8::Gemm g{(const bf16_t*)(ws + WS_HB), (const bf16_t*)(ws + WS_WQ)};
;       pg8::StaticOrder S; S.init(MTOK, DM, G, bx);
;       pg8::EpiNorm E{(bf16_t*)(ws + WS_QN), (const float*)(ws + WS_SUMSQ1), p.xq_g, 1.0f / 16.0f, nullptr};
;       pg8::gemm_phase<pg8::GeoPlain<DM>>(lds, g, S, E); }
.Lea_5:
	s_cmp_eq_u32 s100, 2
	s_cbranch_scc0 .Lepf_5
	v_readlane_b32 s100, v253, 2
	v_readlane_b32 s101, v253, 3
	s_sub_u32 s100, s100, 0x80200
	s_subb_u32 s101, s101, 0
	s_add_u32 s100, s100, 0xb00000
	s_addc_u32 s101, s101, 0
	s_lshr_b32 s99, s2, 3
	s_lshl_b32 s99, s99, 6
	v_and_b32_e32 v224, 63, v208
	v_add_u32_e32 v224, s99, v224
	v_lshrrev_b32_e32 v225, 3, v224
	v_and_b32_e32 v224, 7, v224
	v_lshlrev_b32_e32 v224, 7, v224
	v_lshl_add_u32 v224, v225, 11, v224
	global_load_dword v226, v224, s[100:101]
	v_add_u32_e32 v224, 0x80000, v224
	global_load_dword v226, v224, s[100:101]
	v_add_u32_e32 v224, 0x80000, v224
	global_load_dword v226, v224, s[100:101]
	v_add_u32_e32 v224, 0x80000, v224
	global_load_dword v226, v224, s[100:101]

; #define GSYNC() xcd_barrier(xbar)
; __global__ void __launch_bounds__(512, 2) fwd_megakernel(Params p) {
;     ...
;     GSYNC();
;     { pg8::Gemm g{(const bf16_t*)(ws + WS_P), (const bf16_t*)(ws + WS_VWT)};
;       pg8::StaticOrder S; S.init(MTOK, DM, G, bx);
;       pg8::EpiRes<true, false, true> E{(const void*)(ws + WS_HB), nullptr, (bf16_t*)(ws + WS_HB), (float*)(ws + WS_SUMSQ2)};
;       pg8::gemm_phase<pg8::Geo<DM, DM, 4 * DM, 0, 256L * 4 * DM, DM, 5>>(lds, g, S, E); }
.Lea_6:
	s_cmp_eq_u32 s100, 2
	s_cbranch_scc0 .Lepf_6
	v_readlane_b32 s100, v253, 2
	v_readlane_b32 s101, v253, 3
	s_sub_u32 s100, s100, 0x80200
	s_subb_u32 s101, s101, 0
	s_add_u32 s100, s100, 0x1e000000
	s_addc_u32 s101, s101, 0
	s_and_b32 s99, s2, 7
	s_lshr_b32 s99, s99, 1
	s_lshl_b32 s99, s99, 11
	s_add_u32 s100, s100, s99
	s_addc_u32 s101, s101, 0
	s_lshr_b32 s99, s2, 3
	s_lshl_b32 s99, s99, 6
	v_and_b32_e32 v224, 63, v208
	v_add_u32_e32 v224, s99, v224
	v_lshrrev_b32_e32 v225, 3, v224
	v_and_b32_e32 v224, 7, v224
	v_lshlrev_b32_e32 v224, 7, v224
	v_lshl_add_u32 v224, v225, 13, v224
	global_load_dword v226, v224, s[100:101]
	v_add_u32_e32 v224, 0x200000, v224
	global_load_dword v226, v224, s[100:101]
	v_add_u32_e32 v224, 0x200000, v224
	global_load_dword v226, v224, s[100:101]
	v_add_u32_e32 v224, 0x200000, v224
	global_load_dword v226, v224, s[100:101]

; #define GSYNC() xcd_barrier(xbar)
; __global__ void __launch_bounds__(512, 2) fwd_megakernel(Params p) {
;     ...
;     GSYNC();
;     for (int rep = 0; rep < (PROBE_ID == 9 ? 2 : 1); ++rep) {
;     { pg8::Gemm g{(const bf16_t*)(ws + WS_HB), (const bf16_t*)(ws + WS_W1)};
;       pg8::StaticOrder S; S.init(MTOK, FF, G, bx);
;       pg8::EpiBf<FF, 1, true, -1> E{(bf16_t*)(ws + WS_U), (const float*)(ws + WS_SUMSQ2), nullptr};
;       pg8::gemm_phase<pg8::GeoPlain<DM>>(lds, g, S, E); }
.Lea_7:
	s_cmp_eq_u32 s100, 2
	s_cbranch_scc0 .Lepf_7
	v_readlane_b32 s100, v253, 2
	v_readlane_b32 s101, v253, 3
	s_sub_u32 s100, s100, 0x80200
	s_subb_u32 s101, s101, 0
	s_add_u32 s100, s100, 0x1300000
	s_addc_u32 s101, s101, 0
	s_lshr_b32 s99, s2, 3
	s_lshl_b32 s99, s99, 6
	v_and_b32_e32 v224, 63, v208
	v_add_u32_e32 v224, s99, v224
	v_lshrrev_b32_e32 v225, 3, v224
	v_and_b32_e32 v224, 7, v224
	v_lshlrev_b32_e32 v224, 7, v224
	v_lshl_add_u32 v224, v225, 11, v224
	global_load_dword v226, v224, s[100:101]
	v_add_u32_e32 v224, 0x80000, v224
	global_load_dword v226, v224, s[100:101]
	v_add_u32_e32 v224, 0x80000, v224
	global_load_dword v226, v224, s[100:101]
	v_add_u32_e32 v224, 0x80000, v224
	global_load_dword v226, v224, s[100:101]
	v_add_u32_e32 v224, 0x80000, v224
	global_load_dword v226, v224, s[100:101]
	v_add_u32_e32 v224, 0x80000, v224
	global_load_dword v226, v224, s[100:101]
	v_add_u32_e32 v224, 0x80000, v224
	global_load_dword v226, v224, s[100:101]
	v_add_u32_e32 v224, 0x80000, v224
	global_load_dword v226, v224, s[100:101]

; #define GSYNC() xcd_barrier(xbar)
; __global__ void __launch_bounds__(512, 2) fwd_megakernel(Params p) {
;     ...
;     GSYNC();
;     { pg8::Gemm g{(const bf16_t*)(ws + WS_U), (const bf16_t*)(ws + WS_W2)};
;       pg8::StaticOrder S; S.init(MTOK, DM, G, bx);
;       pg8::EpiRes<true, true, false> E{(const void*)(ws + WS_HB), p.out, nullptr, nullptr};
;       pg8::gemm_phase<pg8::GeoPlain<FF>>(lds, g, S, E); }
.Lea_8:
	s_cmp_eq_u32 s100, 2
	s_cbranch_scc0 .Lepf_8
	v_readlane_b32 s100, v253, 2
	v_readlane_b32 s101, v253, 3
	s_sub_u32 s100, s100, 0x80200
	s_subb_u32 s101, s101, 0
	s_add_u32 s100, s100, 0x1b00000
	s_addc_u32 s101, s101, 0
	s_lshr_b32 s99, s2, 3
	s_lshl_b32 s99, s99, 6
	v_and_b32_e32 v224, 63, v208
	v_add_u32_e32 v224, s99, v224
	v_lshrrev_b32_e32 v225, 3, v224
	v_and_b32_e32 v224, 7, v224
	v_lshlrev_b32_e32 v224, 7, v224
	v_lshl_add_u32 v224, v225, 13, v224
	global_load_dword v226, v224, s[100:101]
	v_add_u32_e32 v224, 0x200000, v224
	global_load_dword v226, v224, s[100:101]
	v_add_u32_e32 v224, 0x200000, v224
	global_load_dword v226, v224, s[100:101]
	v_add_u32_e32 v224, 0x200000, v224
	global_load_dword v226, v224, s[100:101]
